# phase-4 attention: gate block loaded coalesced and transposed through wave-private LDS in the epilogue (same as phase 3)
# baseline (speedup 1.0000x reference)
.Lat4_m5skip:
	s_or_b64 exec, exec, s[18:19]
	v_and_b32_e32 v4, 31, v172
	v_and_b32_e32 v5, 0xffffffc0, v172
	v_or_b32_e32 v6, v13, v4
	v_ashrrev_i32_e32 v7, 31, v6
	v_lshl_add_u32 v118, v0, 8, v5
	v_lshl_add_u32 v2, v12, 1, v0
	v_lshlrev_b64 v[8:9], 10, v[6:7]
	v_ashrrev_i32_e32 v119, 31, v118
	v_lshlrev_b64 v[6:7], 11, v[6:7]
	v_bfe_u32 v22, v172, 5, 1
	v_ashrrev_i32_e32 v3, 31, v2
	v_readlane_b32 s18, v252, 51
	v_lshlrev_b64 v[12:13], 1, v[118:119]
	v_lshl_add_u64 v[120:121], s[88:89], 0, v[6:7]
	v_lshlrev_b64 v[10:11], 18, v[2:3]
	v_readlane_b32 s19, v252, 52
	v_lshlrev_b32_e32 v0, 3, v22
	v_lshl_add_u64 v[6:7], v[120:121], 0, v[12:13]
	v_lshl_add_u64 v[2:3], s[18:19], 0, v[10:11]
	v_lshl_add_u64 v[6:7], v[6:7], 0, v[0:1]
	s_mov_b64 s[18:19], 0x12e80400
	v_lshl_add_u64 v[16:17], v[6:7], 0, s[18:19]
	s_mov_b32 s18, 0x12e80000
	v_add_co_u32_e32 v18, vcc, s18, v6
	v_lshl_add_u64 v[8:9], s[8:9], 0, v[8:9]
	s_nop 0
	v_addc_co_u32_e32 v19, vcc, 0, v7, vcc
	v_lshl_add_u64 v[8:9], v[8:9], 0, v[12:13]
	v_lshlrev_b32_e32 v124, 4, v22
	v_mov_b32_e32 v125, v1
	v_lshl_add_u64 v[6:7], v[2:3], 0, v[164:165]
	v_mov_b32_e32 v169, v1
	v_cmp_lt_i32_e32 vcc, 0, v130
	v_lshl_add_u64 v[14:15], v[8:9], 0, v[124:125]
	v_lshl_add_u64 v[6:7], v[6:7], 0, v[168:169]
	v_lshl_add_u64 v[20:21], v[166:167], 0, v[10:11]
	v_cndmask_b32_e64 v0, 0, 64, vcc
	global_load_dwordx4 v[80:83], v[14:15], off offset:32
	global_load_dwordx4 v[84:87], v[14:15], off offset:64
	global_load_dwordx4 v[88:91], v[14:15], off offset:96
	v_and_b32_e32 v216, 31, v198
	v_lshrrev_b32_e32 v217, 5, v198
	v_lshlrev_b32_e32 v217, 3, v217
	v_lshrrev_b32_e32 v218, 3, v198
	v_and_b32_e32 v219, 7, v198
	v_sub_u32_e32 v220, v218, v216
	v_lshlrev_b32_e32 v220, 11, v220
	v_lshl_add_u32 v220, v219, 4, v220
	v_sub_u32_e32 v220, v220, v217
	v_ashrrev_i32_e32 v221, 31, v220
	v_lshl_add_u64 v[222:223], v[16:17], 0, v[220:221]
	v_lshrrev_b32_e32 v218, 4, v198
	v_and_b32_e32 v219, 15, v198
	v_sub_u32_e32 v220, v218, v216
	v_add_u32_e32 v220, 24, v220
	v_lshlrev_b32_e32 v220, 11, v220
	v_lshl_add_u32 v220, v219, 3, v220
	v_sub_u32_e32 v220, v220, v217
	v_ashrrev_i32_e32 v221, 31, v220
	v_lshl_add_u64 v[218:219], v[16:17], 0, v[220:221]
	v_mov_b32_e32 v220, 0x4000
	v_mov_b32_e32 v221, 0
	global_load_dwordx4 v[104:107], v[222:223], off
	v_lshl_add_u64 v[222:223], v[222:223], 0, v[220:221]
	global_load_dwordx4 v[108:111], v[222:223], off
	v_lshl_add_u64 v[222:223], v[222:223], 0, v[220:221]
	global_load_dwordx4 v[112:115], v[222:223], off
	v_mov_b32_e32 v220, 0x2000
	global_load_dwordx2 v[116:117], v[218:219], off
	v_lshl_add_u64 v[218:219], v[218:219], 0, v[220:221]
	global_load_dwordx2 v[122:123], v[218:219], off
	v_lshl_add_u64 v[126:127], v[20:21], 0, v[168:169]
	global_load_dwordx4 v[6:9], v[6:7], off
	s_nop 0
	global_load_dwordx4 v[92:95], v[14:15], off
	global_load_dwordx4 v[10:13], v[126:127], off
	v_min_i32_e32 v5, 2, v130
	v_add_u32_e32 v14, v0, v162
	v_ashrrev_i32_e32 v15, 31, v14
	v_lshlrev_b32_e32 v16, 6, v5
	v_lshlrev_b64 v[14:15], 7, v[14:15]
	v_add_u32_e32 v18, v16, v162
	v_lshl_add_u64 v[14:15], v[2:3], 0, v[14:15]
	v_ashrrev_i32_e32 v19, 31, v18
	v_ashrrev_i32_e32 v17, 31, v16
	v_lshl_add_u64 v[14:15], v[14:15], 0, v[168:169]
	v_lshlrev_b32_e32 v0, 1, v0
	v_lshlrev_b64 v[18:19], 7, v[18:19]
	v_lshl_add_u64 v[16:17], v[16:17], 1, v[20:21]
	global_load_dwordx4 v[48:51], v[14:15], off
	v_lshl_add_u64 v[14:15], v[20:21], 0, v[0:1]
	v_lshl_add_u64 v[18:19], v[2:3], 0, v[18:19]
	v_lshl_add_u64 v[16:17], v[16:17], 0, v[168:169]
	v_lshl_add_u64 v[14:15], v[14:15], 0, v[168:169]
	v_lshl_add_u64 v[18:19], v[18:19], 0, v[168:169]
	global_load_dwordx4 v[96:99], v[16:17], off
	global_load_dwordx4 v[52:55], v[14:15], off
	global_load_dwordx4 v[100:103], v[18:19], off
	s_waitcnt vmcnt(15)
	s_movk_i32 s18, 0x420
	v_cmp_gt_i32_e32 vcc, s18, v172
	s_and_saveexec_b64 s[18:19], vcc
	ds_write_b64 v210, v[208:209]
	s_or_b64 exec, exec, s[18:19]
	s_movk_i32 s18, 0x320
	v_cmp_gt_i32_e32 vcc, s18, v172
	s_and_saveexec_b64 s[18:19], vcc
	ds_write_b64 v210, v[200:201] offset:2048
	s_or_b64 exec, exec, s[18:19]
	s_movk_i32 s18, 0x220
	v_cmp_gt_i32_e32 vcc, s18, v172
	s_and_saveexec_b64 s[18:19], vcc
	ds_write_b64 v210, v[202:203] offset:4096
	s_or_b64 exec, exec, s[18:19]
	s_movk_i32 s18, 0x120
	v_cmp_gt_i32_e32 vcc, s18, v172
	s_and_saveexec_b64 s[18:19], vcc
	ds_write_b64 v210, v[204:205] offset:6144
	s_or_b64 exec, exec, s[18:19]
	v_cmp_gt_i32_e32 vcc, 32, v172
	s_and_saveexec_b64 s[18:19], vcc
	ds_write_b64 v210, v[206:207] offset:8192
	s_or_b64 exec, exec, s[18:19]
	v_cmp_lt_i32_e32 vcc, -1, v130
	v_mov_b32_e32 v47, 0
	v_mov_b32_e32 v46, 0
	v_mov_b32_e32 v45, 0
	v_mov_b32_e32 v44, 0
	v_mov_b32_e32 v43, 0
	v_mov_b32_e32 v42, 0
	v_mov_b32_e32 v41, 0
	v_mov_b32_e32 v40, 0
	v_mov_b32_e32 v39, 0
	v_mov_b32_e32 v38, 0
	v_lshlrev_b32_e32 v125, 2, v22
	v_mov_b32_e32 v37, 0
	v_mov_b32_e32 v36, 0
	v_mov_b32_e32 v35, 0
	v_mov_b32_e32 v34, 0
	v_mov_b32_e32 v33, 0
	v_mov_b32_e32 v32, 0
	v_mov_b32_e32 v31, 0
	v_mov_b32_e32 v30, 0
	v_mov_b32_e32 v29, 0
	v_mov_b32_e32 v28, 0
	v_mov_b32_e32 v27, 0
	v_mov_b32_e32 v26, 0
	v_mov_b32_e32 v25, 0
	v_mov_b32_e32 v24, 0
	v_mov_b32_e32 v23, 0
	v_mov_b32_e32 v22, 0
	s_waitcnt vmcnt(6)
	ds_write_b128 v163, v[6:9]
	s_waitcnt vmcnt(4)
	ds_write_b128 v184, v[10:13]
	v_mov_b32_e32 v21, 0
	v_mov_b32_e32 v20, 0
	v_mov_b32_e32 v19, 0
	v_mov_b32_e32 v18, 0
	v_mov_b32_e32 v17, 0
	v_mov_b32_e32 v16, 0
	v_mov_b32_e32 v10, 0
	s_waitcnt lgkmcnt(0)
	s_barrier
	s_and_saveexec_b64 s[18:19], vcc
	s_cbranch_execz .LBB0_907
	v_mov_b32_e32 v14, v1
	v_mov_b32_e32 v15, v1
	v_lshl_add_u64 v[128:129], v[2:3], 0, v[168:169]
	v_mul_u32_u24_e32 v131, 0x90, v4
	v_mad_u32_u24 v132, v4, s33, v182
	v_mov_b32_e32 v0, v1
	v_mov_b32_e32 v2, v1
	v_mov_b32_e32 v3, v1
	v_mov_b32_e32 v4, v1
	v_mov_b32_e32 v5, v1
	v_mov_b32_e32 v6, v1
	v_mov_b32_e32 v7, v1
	v_mov_b32_e32 v8, v1
	v_mov_b32_e32 v9, v1
	v_mov_b32_e32 v10, v1
	v_mov_b32_e32 v11, v1
	v_mov_b32_e32 v12, v1
	v_mov_b32_e32 v13, v1
	v_mov_b64_e32 v[30:31], v[14:15]
	v_mov_b64_e32 v[46:47], v[14:15]
	v_add_u32_e32 v133, 1, v130
	s_mov_b32 s37, 0
	v_mov_b32_e32 v135, 0xf149f2ca
	v_mov_b32_e32 v134, 0
	s_mov_b64 s[20:21], 0
	v_mov_b64_e32 v[28:29], v[12:13]
	v_mov_b64_e32 v[26:27], v[10:11]
	v_mov_b64_e32 v[24:25], v[8:9]
	v_mov_b64_e32 v[22:23], v[6:7]
	v_mov_b64_e32 v[20:21], v[4:5]
	v_mov_b64_e32 v[18:19], v[2:3]
	v_mov_b64_e32 v[16:17], v[0:1]
	v_mov_b64_e32 v[44:45], v[12:13]
	v_mov_b64_e32 v[42:43], v[10:11]
	v_mov_b64_e32 v[40:41], v[8:9]
	v_mov_b64_e32 v[38:39], v[6:7]
	v_mov_b64_e32 v[36:37], v[4:5]
	v_mov_b64_e32 v[34:35], v[2:3]
	v_mov_b64_e32 v[32:33], v[0:1]
	s_branch .LBB0_902

.LBB0_907:
	s_or_b64 exec, exec, s[18:19]
	v_lshrrev_b32_e32 v216, 6, v172
	v_mul_u32_u24_e32 v216, 0x1200, v216
	v_add_u32_e32 v216, v216, v182
	v_add_u32_e32 v216, 0x3000, v216
	v_lshrrev_b32_e32 v220, 3, v198
	v_and_b32_e32 v221, 7, v198
	v_mul_u32_u24_e32 v217, 0x90, v220
	v_lshl_add_u32 v217, v221, 4, v217
	v_add_u32_e32 v217, v217, v216
	v_lshrrev_b32_e32 v220, 4, v198
	v_and_b32_e32 v221, 15, v198
	v_mul_u32_u24_e32 v222, 0x90, v220
	v_lshl_add_u32 v222, v221, 3, v222
	v_add_u32_e32 v222, v222, v216
	v_and_b32_e32 v218, 31, v198
	v_lshrrev_b32_e32 v219, 5, v198
	v_mul_u32_u24_e32 v223, 0x90, v218
	v_lshl_add_u32 v223, v219, 3, v223
	v_add_u32_e32 v216, v223, v216
	ds_write_b128 v217, v[104:107]
	ds_write_b128 v217, v[108:111] offset:1152
	ds_write_b128 v217, v[112:115] offset:2304
	ds_write_b64 v222, v[116:117] offset:3456
	ds_write_b64 v222, v[122:123] offset:4032
	s_waitcnt lgkmcnt(0)
	ds_read_b64 v[122:123], v216
	ds_read_b64 v[116:117], v216 offset:16
	ds_read_b64 v[114:115], v216 offset:32
	ds_read_b64 v[112:113], v216 offset:48
	ds_read_b64 v[110:111], v216 offset:64
	ds_read_b64 v[108:109], v216 offset:80
	ds_read_b64 v[106:107], v216 offset:96
	ds_read_b64 v[104:105], v216 offset:112
	s_waitcnt lgkmcnt(0)
	ds_bpermute_b32 v0, v234, v10
	s_waitcnt vmcnt(6)
	v_and_b32_e32 v5, 0xffff0000, v122
	v_lshlrev_b32_e32 v4, 16, v122
	v_lshl_add_u64 v[2:3], v[118:119], 1, v[120:121]
	s_waitcnt lgkmcnt(0)
	v_add_f32_e32 v0, v10, v0
	v_max_f32_e32 v0, 0xda24260, v0
	v_div_scale_f32 v6, s[18:19], v0, v0, 1.0
	v_rcp_f32_e32 v7, v6
	v_div_scale_f32 v8, vcc, 1.0, v0, 1.0
	s_mov_b64 s[18:19], 0x16f80400
	v_fma_f32 v9, -v6, v7, 1.0
	v_fmac_f32_e32 v7, v9, v7
	v_mul_f32_e32 v9, v8, v7
	v_fma_f32 v10, -v6, v9, v8
	v_fmac_f32_e32 v9, v10, v7
	v_fma_f32 v6, -v6, v9, v8
	v_div_fmas_f32 v6, v6, v7, v9
	v_div_fixup_f32 v6, v6, v0, 1.0
	v_pk_mul_f32 v[8:9], v[32:33], v[6:7] op_sel_hi:[1,0]
	v_pk_mul_f32 v[10:11], v[34:35], v[6:7] op_sel_hi:[1,0]
	v_pk_mul_f32 v[4:5], v[8:9], v[4:5]
	v_and_b32_e32 v9, 0xffff0000, v123
	v_lshlrev_b32_e32 v8, 16, v123
	v_lshlrev_b32_e32 v0, 1, v125
	v_pk_mul_f32 v[8:9], v[10:11], v[8:9]
	v_lshl_add_u64 v[2:3], v[2:3], 0, v[0:1]
	v_cvt_pk_bf16_f32 v4, v4, v5
	v_cvt_pk_bf16_f32 v5, v8, v9
	v_lshl_add_u64 v[8:9], v[2:3], 0, s[18:19]
	s_mov_b32 s18, 0x16f80000
	v_add_co_u32_e32 v2, vcc, s18, v2
	v_pk_mul_f32 v[10:11], v[38:39], v[6:7] op_sel_hi:[1,0]
	s_nop 0
	v_addc_co_u32_e32 v3, vcc, 0, v3, vcc
	v_lshrrev_b32_e32 v216, 6, v172
	v_mul_u32_u24_e32 v216, 0x1200, v216
	v_add_u32_e32 v216, v216, v182
	v_add_u32_e32 v216, 0x3000, v216
	v_and_b32_e32 v218, 31, v198
	v_lshrrev_b32_e32 v219, 5, v198
	v_lshrrev_b32_e32 v220, 3, v198
	v_and_b32_e32 v221, 7, v198
	v_mul_u32_u24_e32 v222, 0x90, v220
	v_lshl_add_u32 v222, v221, 4, v222
	v_add_u32_e32 v217, v222, v216
	v_mul_u32_u24_e32 v222, 0x90, v218
	v_lshl_add_u32 v222, v219, 3, v222
	v_add_u32_e32 v216, v222, v216
	v_sub_u32_e32 v220, v220, v218
	v_lshlrev_b32_e32 v220, 11, v220
	v_lshl_add_u32 v220, v221, 4, v220
	v_lshlrev_b32_e32 v219, 3, v219
	v_sub_u32_e32 v220, v220, v219
	v_ashrrev_i32_e32 v221, 31, v220
	v_lshl_add_u64 v[218:219], v[8:9], 0, v[220:221]
	ds_write_b64 v216, v[4:5]
	v_and_b32_e32 v3, 0xffff0000, v116
	v_lshlrev_b32_e32 v2, 16, v116
	v_pk_mul_f32 v[4:5], v[36:37], v[6:7] op_sel_hi:[1,0]
	s_nop 0
	v_pk_mul_f32 v[2:3], v[4:5], v[2:3]
	v_and_b32_e32 v5, 0xffff0000, v117
	v_lshlrev_b32_e32 v4, 16, v117
	v_pk_mul_f32 v[4:5], v[10:11], v[4:5]
	v_cvt_pk_bf16_f32 v2, v2, v3
	v_cvt_pk_bf16_f32 v3, v4, v5
	ds_write_b64 v216, v[2:3] offset:16
	v_and_b32_e32 v3, 0xffff0000, v114
	v_lshlrev_b32_e32 v2, 16, v114
	v_pk_mul_f32 v[4:5], v[40:41], v[6:7] op_sel_hi:[1,0]
	v_pk_mul_f32 v[10:11], v[42:43], v[6:7] op_sel_hi:[1,0]
	v_pk_mul_f32 v[2:3], v[4:5], v[2:3]
	v_and_b32_e32 v5, 0xffff0000, v115
	v_lshlrev_b32_e32 v4, 16, v115
	v_pk_mul_f32 v[4:5], v[10:11], v[4:5]
	v_cvt_pk_bf16_f32 v2, v2, v3
	v_cvt_pk_bf16_f32 v3, v4, v5
	ds_write_b64 v216, v[2:3] offset:32
	v_and_b32_e32 v3, 0xffff0000, v112
	v_lshlrev_b32_e32 v2, 16, v112
	v_pk_mul_f32 v[4:5], v[44:45], v[6:7] op_sel_hi:[1,0]
	v_pk_mul_f32 v[10:11], v[46:47], v[6:7] op_sel_hi:[1,0]
	v_pk_mul_f32 v[2:3], v[4:5], v[2:3]
	v_and_b32_e32 v5, 0xffff0000, v113
	v_lshlrev_b32_e32 v4, 16, v113
	v_pk_mul_f32 v[4:5], v[10:11], v[4:5]
	v_cvt_pk_bf16_f32 v2, v2, v3
	v_cvt_pk_bf16_f32 v3, v4, v5
	ds_write_b64 v216, v[2:3] offset:48
	v_and_b32_e32 v3, 0xffff0000, v110
	v_lshlrev_b32_e32 v2, 16, v110
	v_pk_mul_f32 v[4:5], v[16:17], v[6:7] op_sel_hi:[1,0]
	v_pk_mul_f32 v[10:11], v[18:19], v[6:7] op_sel_hi:[1,0]
	v_pk_mul_f32 v[2:3], v[4:5], v[2:3]
	v_and_b32_e32 v5, 0xffff0000, v111
	v_lshlrev_b32_e32 v4, 16, v111
	v_pk_mul_f32 v[4:5], v[10:11], v[4:5]
	v_cvt_pk_bf16_f32 v2, v2, v3
	v_cvt_pk_bf16_f32 v3, v4, v5
	ds_write_b64 v216, v[2:3] offset:64
	v_and_b32_e32 v3, 0xffff0000, v108
	v_lshlrev_b32_e32 v2, 16, v108
	v_pk_mul_f32 v[4:5], v[20:21], v[6:7] op_sel_hi:[1,0]
	v_pk_mul_f32 v[10:11], v[22:23], v[6:7] op_sel_hi:[1,0]
	v_pk_mul_f32 v[2:3], v[4:5], v[2:3]
	v_and_b32_e32 v5, 0xffff0000, v109
	v_lshlrev_b32_e32 v4, 16, v109
	v_pk_mul_f32 v[4:5], v[10:11], v[4:5]
	v_cvt_pk_bf16_f32 v2, v2, v3
	v_cvt_pk_bf16_f32 v3, v4, v5
	ds_write_b64 v216, v[2:3] offset:80
	s_waitcnt vmcnt(5)
	v_and_b32_e32 v3, 0xffff0000, v106
	v_lshlrev_b32_e32 v2, 16, v106
	v_pk_mul_f32 v[4:5], v[24:25], v[6:7] op_sel_hi:[1,0]
	v_pk_mul_f32 v[10:11], v[26:27], v[6:7] op_sel_hi:[1,0]
	v_pk_mul_f32 v[2:3], v[4:5], v[2:3]
	v_and_b32_e32 v5, 0xffff0000, v107
	v_lshlrev_b32_e32 v4, 16, v107
	v_pk_mul_f32 v[4:5], v[10:11], v[4:5]
	v_cvt_pk_bf16_f32 v2, v2, v3
	v_cvt_pk_bf16_f32 v3, v4, v5
	ds_write_b64 v216, v[2:3] offset:96
	s_waitcnt vmcnt(4)
	v_and_b32_e32 v3, 0xffff0000, v104
	v_lshlrev_b32_e32 v2, 16, v104
	v_pk_mul_f32 v[4:5], v[28:29], v[6:7] op_sel_hi:[1,0]
	v_pk_mul_f32 v[6:7], v[30:31], v[6:7] op_sel_hi:[1,0]
	v_pk_mul_f32 v[2:3], v[4:5], v[2:3]
	v_and_b32_e32 v5, 0xffff0000, v105
	v_lshlrev_b32_e32 v4, 16, v105
	v_pk_mul_f32 v[4:5], v[6:7], v[4:5]
	v_cvt_pk_bf16_f32 v2, v2, v3
	v_cvt_pk_bf16_f32 v3, v4, v5
	ds_write_b64 v216, v[2:3] offset:112
	s_waitcnt lgkmcnt(0)
	ds_read_b128 v[200:203], v217
	ds_read_b128 v[204:207], v217 offset:1152
	ds_read_b128 v[208:211], v217 offset:2304
	ds_read_b128 v[212:215], v217 offset:3456
	v_mov_b32_e32 v220, 0x4000
	v_mov_b32_e32 v221, 0
	s_waitcnt lgkmcnt(3)
	global_store_dwordx4 v[218:219], v[200:203], off
	v_lshl_add_u64 v[218:219], v[218:219], 0, v[220:221]
	s_waitcnt lgkmcnt(2)
	global_store_dwordx4 v[218:219], v[204:207], off
	v_lshl_add_u64 v[218:219], v[218:219], 0, v[220:221]
	s_waitcnt lgkmcnt(1)
	global_store_dwordx4 v[218:219], v[208:211], off
	v_lshl_add_u64 v[218:219], v[218:219], 0, v[220:221]
	s_waitcnt lgkmcnt(0)
	global_store_dwordx4 v[218:219], v[212:215], off
	s_barrier
